# kernel-start grid sync: control-word zeroing stores write-through (sc1) and drained per wave, so the release-side buffer_wbl2 goes; the acquire-side buffer_inv issued behind the arrival instead of aft
# speedup vs baseline: 1.0037x; 1.0037x over previous
; #define GAS __attribute__((address_space(1)))
; __global__ void __launch_bounds__(NWAVES * 64, 2) hybrid_fwd(const Args A) {
;     ...
;         if (blockIdx.x == 0) { GAS v4u* z = (GAS v4u*)(F.ws + WS_CTL); for (int i = F.tid; i < (int)(CTL_ZERO_BYTES / 16); i += NWAVES * 64) if (i < (int)(WS_PRM / 16) || i >= (int)((CW_SEAM * 4) / 16)) z[i] = (v4u){0u, 0u, 0u, 0u}; }
;         grid.sync();
.LBB0_10:
	s_or_b64 exec, exec, s[4:5]
	v_lshrrev_b32_e32 v2, 20, v0
	v_lshrrev_b32_e32 v0, 10, v0
	v_or_b32_e32 v0, v0, v2
	s_movk_i32 s4, 0x3ff
	v_and_or_b32 v0, v0, s4, v1
	v_cmp_eq_u32_e32 vcc, 0, v0
	s_waitcnt vmcnt(0)
	s_barrier
	s_and_saveexec_b64 s[4:5], vcc
	s_cbranch_execz .LBB0_20
	s_waitcnt vmcnt(0)
	s_load_dwordx2 s[2:3], s[2:3], 0x58
	v_mov_b32_e32 v2, 0
	s_mov_b64 s[6:7], exec
	v_mbcnt_lo_u32_b32 v1, s6, 0
	v_mbcnt_hi_u32_b32 v1, s7, v1
	s_waitcnt lgkmcnt(0)
	global_load_dword v0, v2, s[2:3] offset:40
	v_cmp_eq_u32_e32 vcc, 0, v1
	s_and_saveexec_b64 s[8:9], vcc
	s_cbranch_execz .LBB0_13
	s_bcnt1_i32_b64 s6, s[6:7]
	v_mov_b32_e32 v3, s6
	global_atomic_add v3, v2, v3, s[2:3] offset:32 sc0

; __global__ void __launch_bounds__(NWAVES * 64, 2) hybrid_fwd(const Args A) {
;     ...
;         grid.sync();
.LBB0_16:
	s_or_b64 exec, exec, s[6:7]
	buffer_inv sc1
	v_mov_b32_e32 v0, 0
	global_load_dword v2, v0, s[2:3] offset:32 sc1
	v_and_b32_e32 v1, 0xffff0000, v1
	s_waitcnt vmcnt(0)
	v_and_b32_e32 v2, 0xffff0000, v2
	v_cmp_eq_u32_e32 vcc, v2, v1
	s_and_b64 exec, exec, vcc
	s_cbranch_execz .LBB0_19
	s_mov_b64 s[6:7], 0

; __device__ __forceinline__ int lane_id_asm() { int l; asm volatile("v_mbcnt_lo_u32_b32 %0, -1, 0\n\tv_mbcnt_hi_u32_b32 %0, -1, %0" : "=v"(l)); return l; }
; #define LAS __attribute__((address_space(3)))
; __device__ __forceinline__ unsigned xb_add(unsigned* p, unsigned v) { return __hip_atomic_fetch_add(p, v, __ATOMIC_RELAXED, __HIP_MEMORY_SCOPE_AGENT); }
; __device__ __forceinline__ unsigned xb_xcc_id() { return (unsigned)__builtin_amdgcn_s_getreg((3 << 11) | 20) & 0xFu; }
; __device__ __forceinline__ XcdBarrier xcd_barrier_post(unsigned* bar, volatile LAS unsigned* st, const int wid) {
;     XcdBarrier b; b.bar = bar; b.x = xb_xcc_id(); b.st = st;
;     if (wid == 0 && lane_id_asm() == 0) (void)xb_add(&bar[XB_XCNT(b.x)], 1u);
;     return b;
; __global__ void __launch_bounds__(NWAVES * 64, 2) hybrid_fwd(const Args A) {
;     ...
;         grid.sync();
;         bar = xcd_barrier_post(F.ctl + CW_BAR, MISC + 8, F.wave);
.LBB0_19:
.LBB0_20:
	s_or_b64 exec, exec, s[4:5]
	s_barrier
	s_getreg_b32 s2, hwreg(HW_REG_XCC_ID, 0, 4)
	s_and_b32 s2, s2, 15
	v_writelane_b32 v254, s2, 8
	s_cmp_gt_u32 s79, 63
	s_cbranch_scc1 .LBB0_25
	v_mbcnt_lo_u32_b32 v0, -1, 0
	v_mbcnt_hi_u32_b32 v0, -1, v0
	s_nop 0
	v_cmp_eq_u32_e32 vcc, 0, v0
	s_and_saveexec_b64 s[2:3], vcc
	s_cbranch_execz .LBB0_24
	s_mov_b64 s[4:5], exec
	v_mbcnt_lo_u32_b32 v0, s4, 0
	v_mbcnt_hi_u32_b32 v0, s5, v0
	v_cmp_eq_u32_e32 vcc, 0, v0
	s_and_b64 s[6:7], exec, vcc
	s_mov_b64 exec, s[6:7]
	s_cbranch_execz .LBB0_24
	v_readlane_b32 s6, v254, 8
	s_bcnt1_i32_b64 s4, s[4:5]
	s_lshl_b32 s6, s6, 8
	v_mov_b32_e32 v1, s4
	v_readlane_b32 s4, v254, 6
	v_mov_b32_e32 v0, s6
	v_readlane_b32 s5, v254, 7
	s_nop 4
	global_atomic_add v0, v1, s[4:5] offset:1024
